# k16 + SwiGLU epilogue: the per-element sigmoid argument multiply and the +1.0 add done as packed f32 pairs (same arithmetic, fewer VALU issues)
# baseline (speedup 1.0000x reference)
.Lpeel_exit_445:
.LBB0_448:
	s_mov_b32 s100, 0xbfb8aa3b
	s_mov_b32 s101, s100
	v_mov_b32_e32 v0, v145
	v_mov_b32_e32 v130, v134
	s_lshl_b32 s25, s24, 7
	s_or_b32 s25, s25, s74
	s_mul_i32 s46, s71, 0x180000
	v_add_u32_e32 v149, s41, v130
	v_lshl_add_u32 v130, v0, 3, s25
	s_mul_hi_i32 s25, s71, 0x180000
	s_add_u32 s46, s67, s46
	s_addc_u32 s47, s68, s25
	s_lshl_b32 s24, s24, 3
	s_or_b32 s24, s24, s70
	s_ashr_i32 s25, s24, 31
	s_lshl_b64 s[24:25], s[24:25], 2
	s_add_u32 s24, s26, s24
	s_addc_u32 s25, s69, s25
	global_load_dword v150, v1, s[24:25] sc1
	global_load_dword v151, v1, s[24:25] offset:16 sc1
	v_cvt_f32_i32_e32 v127, v127
	v_cvt_f32_i32_e32 v126, v126
	v_cvt_f32_i32_e32 v129, v129
	v_cvt_f32_i32_e32 v128, v128
	v_cvt_f32_i32_e32 v123, v123
	v_cvt_f32_i32_e32 v122, v122
	v_cvt_f32_i32_e32 v125, v125
	v_cvt_f32_i32_e32 v124, v124
	v_cvt_f32_i32_e32 v119, v119
	v_cvt_f32_i32_e32 v118, v118
	v_cvt_f32_i32_e32 v121, v121
	v_cvt_f32_i32_e32 v120, v120
	v_cvt_f32_i32_e32 v117, v117
	v_cvt_f32_i32_e32 v116, v116
	v_cvt_f32_i32_e32 v115, v115
	v_cvt_f32_i32_e32 v114, v114
	v_ashrrev_i32_e32 v131, 31, v130
	v_lshl_add_u64 v[130:131], v[130:131], 1, s[46:47]
	v_cvt_f32_i32_e32 v105, v105
	v_cvt_f32_i32_e32 v104, v104
	v_cvt_f32_i32_e32 v103, v103
	v_cvt_f32_i32_e32 v102, v102
	v_cvt_f32_i32_e32 v101, v101
	v_cvt_f32_i32_e32 v100, v100
	v_cvt_f32_i32_e32 v99, v99
	v_cvt_f32_i32_e32 v98, v98
	v_cvt_f32_i32_e32 v107, v107
	v_cvt_f32_i32_e32 v106, v106
	v_cvt_f32_i32_e32 v109, v109
	v_cvt_f32_i32_e32 v108, v108
	v_cvt_f32_i32_e32 v95, v95
	v_cvt_f32_i32_e32 v94, v94
	v_cvt_f32_i32_e32 v97, v97
	v_cvt_f32_i32_e32 v96, v96
	v_cvt_f32_i32_e32 v91, v91
	v_cvt_f32_i32_e32 v90, v90
	v_cvt_f32_i32_e32 v93, v93
	v_cvt_f32_i32_e32 v92, v92
	v_cvt_f32_i32_e32 v87, v87
	v_cvt_f32_i32_e32 v86, v86
	v_cvt_f32_i32_e32 v89, v89
	v_cvt_f32_i32_e32 v88, v88
	v_cvt_f32_i32_e32 v79, v79
	v_cvt_f32_i32_e32 v78, v78
	v_cvt_f32_i32_e32 v81, v81
	v_cvt_f32_i32_e32 v80, v80
	v_cvt_f32_i32_e32 v75, v75
	v_cvt_f32_i32_e32 v74, v74
	v_cvt_f32_i32_e32 v77, v77
	v_cvt_f32_i32_e32 v76, v76
	v_cvt_f32_i32_e32 v85, v85
	v_cvt_f32_i32_e32 v84, v84
	v_cvt_f32_i32_e32 v83, v83
	v_cvt_f32_i32_e32 v82, v82
	v_cvt_f32_i32_e32 v71, v71
	v_cvt_f32_i32_e32 v70, v70
	v_cvt_f32_i32_e32 v73, v73
	v_cvt_f32_i32_e32 v72, v72
	v_cvt_f32_i32_e32 v63, v63
	v_cvt_f32_i32_e32 v62, v62
	v_cvt_f32_i32_e32 v65, v65
	v_cvt_f32_i32_e32 v64, v64
	v_cvt_f32_i32_e32 v59, v59
	v_cvt_f32_i32_e32 v58, v58
	v_cvt_f32_i32_e32 v61, v61
	v_cvt_f32_i32_e32 v60, v60
	v_cvt_f32_i32_e32 v69, v69
	v_cvt_f32_i32_e32 v68, v68
	v_cvt_f32_i32_e32 v67, v67
	v_cvt_f32_i32_e32 v66, v66
	v_cvt_f32_i32_e32 v55, v55
	v_cvt_f32_i32_e32 v54, v54
	v_cvt_f32_i32_e32 v57, v57
	v_cvt_f32_i32_e32 v56, v56
	v_cvt_f32_i32_e32 v47, v47
	v_cvt_f32_i32_e32 v46, v46
	v_cvt_f32_i32_e32 v49, v49
	v_cvt_f32_i32_e32 v48, v48
	s_and_b64 vcc, exec, s[10:11]
	s_cbranch_vccz .Lepi_lead_448
	s_barrier
.Lepi_lead_448:
	s_waitcnt vmcnt(0)
	v_mul_f32_e32 v0, v135, v150
	v_pk_mul_f32 v[126:127], v[0:1], v[126:127] op_sel_hi:[0,1]
	v_pk_mul_f32 v[128:129], v[0:1], v[128:129] op_sel_hi:[0,1]
	v_pk_mul_f32 v[124:125], v[0:1], v[124:125] op_sel_hi:[0,1]
	v_pk_mul_f32 v[122:123], v[0:1], v[122:123] op_sel_hi:[0,1]
	v_pk_mul_f32 v[214:215], v[126:127], s[100:101] op_sel_hi:[1,0]
	v_exp_f32_e32 v214, v214
	v_exp_f32_e32 v215, v215
	v_mul_f32_e32 v152, v135, v151
	v_pk_mul_f32 v[118:119], v[152:153], v[118:119] op_sel_hi:[0,1]
	v_pk_mul_f32 v[120:121], v[152:153], v[120:121] op_sel_hi:[0,1]
	v_pk_add_f32 v[214:215], v[214:215], 1.0 op_sel_hi:[1,0]
	v_rcp_f32_e32 v154, v214
	v_pk_mul_f32 v[114:115], v[152:153], v[114:115] op_sel_hi:[0,1]
	v_pk_mul_f32 v[116:117], v[152:153], v[116:117] op_sel_hi:[0,1]
	v_mad_i64_i32 v[152:153], s[24:25], v149, s52, v[130:131]
	v_rcp_f32_e32 v155, v215
	v_pk_mul_f32 v[216:217], v[128:129], s[100:101] op_sel_hi:[1,0]
	v_exp_f32_e32 v216, v216
	v_exp_f32_e32 v217, v217
	v_cvt_f32_i32_e32 v43, v43
	v_pk_mul_f32 v[126:127], v[126:127], v[154:155]
	v_cvt_f32_i32_e32 v42, v42
	v_pk_add_f32 v[216:217], v[216:217], 1.0 op_sel_hi:[1,0]
	v_rcp_f32_e32 v156, v216
	v_pk_mul_f32 v[118:119], v[118:119], v[126:127]
	v_cvt_f32_i32_e32 v45, v45
	v_cvt_f32_i32_e32 v44, v44
	v_rcp_f32_e32 v157, v217
	v_pk_mul_f32 v[218:219], v[122:123], s[100:101] op_sel_hi:[1,0]
	v_exp_f32_e32 v218, v218
	v_exp_f32_e32 v219, v219
	v_cvt_f32_i32_e32 v53, v53
	v_pk_mul_f32 v[128:129], v[128:129], v[156:157]
	v_cvt_f32_i32_e32 v52, v52
	v_pk_add_f32 v[218:219], v[218:219], 1.0 op_sel_hi:[1,0]
	v_rcp_f32_e32 v126, v218
	v_pk_mul_f32 v[120:121], v[120:121], v[128:129]
	v_cvt_f32_i32_e32 v51, v51
	v_cvt_f32_i32_e32 v50, v50
	v_rcp_f32_e32 v127, v219
	v_pk_mul_f32 v[220:221], v[124:125], s[100:101] op_sel_hi:[1,0]
	v_exp_f32_e32 v220, v220
	v_exp_f32_e32 v221, v221
	v_cvt_f32_i32_e32 v39, v39
	v_pk_mul_f32 v[122:123], v[122:123], v[126:127]
	v_cvt_f32_i32_e32 v38, v38
	v_pk_add_f32 v[220:221], v[220:221], 1.0 op_sel_hi:[1,0]
	v_rcp_f32_e32 v128, v220
	v_cvt_f32_i32_e32 v41, v41
	v_cvt_f32_i32_e32 v40, v40
	v_cvt_f32_i32_e32 v31, v31
	v_rcp_f32_e32 v129, v221
	v_mul_f32_e32 v0, v136, v151
	v_pk_mul_f32 v[102:103], v[0:1], v[102:103] op_sel_hi:[0,1]
	v_pk_mul_f32 v[104:105], v[0:1], v[104:105] op_sel_hi:[0,1]
	v_pk_mul_f32 v[124:125], v[124:125], v[128:129]
	v_pk_mul_f32 v[98:99], v[0:1], v[98:99] op_sel_hi:[0,1]
	v_pk_mul_f32 v[124:125], v[116:117], v[124:125]
	v_pk_mul_f32 v[116:117], v[114:115], v[122:123]
	v_cvt_pk_bf16_f32 v114, v118, v119
	v_cvt_pk_bf16_f32 v115, v120, v121
	v_pk_mul_f32 v[100:101], v[0:1], v[100:101] op_sel_hi:[0,1]
	v_cvt_pk_bf16_f32 v116, v116, v117
	v_cvt_pk_bf16_f32 v117, v124, v125
	global_store_dwordx4 v[152:153], v[114:117], off
	v_cvt_f32_i32_e32 v30, v30
	v_cvt_f32_i32_e32 v33, v33
	v_cvt_f32_i32_e32 v117, v111
	v_cvt_f32_i32_e32 v116, v110
	v_add_u32_e32 v115, 16, v149
	v_mul_f32_e32 v114, v136, v150
	v_cvt_f32_i32_e32 v111, v113
	v_cvt_f32_i32_e32 v110, v112
	v_pk_mul_f32 v[112:113], v[114:115], v[116:117] op_sel_hi:[0,1]
	v_pk_mul_f32 v[222:223], v[112:113], s[100:101] op_sel_hi:[1,0]
	v_exp_f32_e32 v222, v222
	v_exp_f32_e32 v223, v223
	v_pk_mul_f32 v[110:111], v[114:115], v[110:111] op_sel_hi:[0,1]
	v_pk_mul_f32 v[106:107], v[114:115], v[106:107] op_sel_hi:[0,1]
	v_pk_mul_f32 v[108:109], v[114:115], v[108:109] op_sel_hi:[0,1]
	v_pk_add_f32 v[222:223], v[222:223], 1.0 op_sel_hi:[1,0]
	v_rcp_f32_e32 v116, v222
	v_mad_i64_i32 v[114:115], s[24:25], v115, s52, v[130:131]
	v_cvt_f32_i32_e32 v32, v32
	v_rcp_f32_e32 v117, v223
	v_pk_mul_f32 v[224:225], v[110:111], s[100:101] op_sel_hi:[1,0]
	v_exp_f32_e32 v224, v224
	v_exp_f32_e32 v225, v225
	v_cvt_f32_i32_e32 v27, v27
	v_pk_mul_f32 v[112:113], v[112:113], v[116:117]
	v_cvt_f32_i32_e32 v26, v26
	v_pk_add_f32 v[224:225], v[224:225], 1.0 op_sel_hi:[1,0]
	v_rcp_f32_e32 v118, v224
	v_pk_mul_f32 v[102:103], v[102:103], v[112:113]
	v_cvt_f32_i32_e32 v29, v29
	v_cvt_f32_i32_e32 v28, v28
	v_rcp_f32_e32 v119, v225
	v_pk_mul_f32 v[226:227], v[106:107], s[100:101] op_sel_hi:[1,0]
	v_exp_f32_e32 v226, v226
	v_exp_f32_e32 v227, v227
	v_cvt_f32_i32_e32 v37, v37
	v_pk_mul_f32 v[110:111], v[110:111], v[118:119]
	v_cvt_f32_i32_e32 v36, v36
	v_pk_add_f32 v[226:227], v[226:227], 1.0 op_sel_hi:[1,0]
	v_pk_mul_f32 v[104:105], v[104:105], v[110:111]
	v_rcp_f32_e32 v110, v226
	v_cvt_f32_i32_e32 v35, v35
	v_cvt_f32_i32_e32 v34, v34
	v_cvt_f32_i32_e32 v23, v23
	v_rcp_f32_e32 v111, v227
	v_pk_mul_f32 v[228:229], v[108:109], s[100:101] op_sel_hi:[1,0]
	v_exp_f32_e32 v228, v228
	v_exp_f32_e32 v229, v229
	v_cvt_f32_i32_e32 v22, v22
	v_pk_mul_f32 v[106:107], v[106:107], v[110:111]
	v_cvt_f32_i32_e32 v25, v25
	v_pk_add_f32 v[228:229], v[228:229], 1.0 op_sel_hi:[1,0]
	v_rcp_f32_e32 v112, v228
	v_cvt_f32_i32_e32 v24, v24
	v_cvt_f32_i32_e32 v15, v15
	v_cvt_f32_i32_e32 v14, v14
	v_rcp_f32_e32 v113, v229
	v_mul_f32_e32 v0, v137, v150
	v_pk_mul_f32 v[94:95], v[0:1], v[94:95] op_sel_hi:[0,1]
	v_pk_mul_f32 v[96:97], v[0:1], v[96:97] op_sel_hi:[0,1]
	v_pk_mul_f32 v[92:93], v[0:1], v[92:93] op_sel_hi:[0,1]
	v_pk_mul_f32 v[90:91], v[0:1], v[90:91] op_sel_hi:[0,1]
	v_pk_mul_f32 v[214:215], v[94:95], s[100:101] op_sel_hi:[1,0]
	v_exp_f32_e32 v214, v214
	v_exp_f32_e32 v215, v215
	v_pk_mul_f32 v[108:109], v[108:109], v[112:113]
	v_cvt_f32_i32_e32 v17, v17
	v_pk_mul_f32 v[108:109], v[100:101], v[108:109]
	v_pk_mul_f32 v[100:101], v[98:99], v[106:107]
	v_cvt_pk_bf16_f32 v98, v102, v103
	v_cvt_pk_bf16_f32 v99, v104, v105
	v_pk_add_f32 v[214:215], v[214:215], 1.0 op_sel_hi:[1,0]
	v_cvt_pk_bf16_f32 v100, v100, v101
	v_cvt_pk_bf16_f32 v101, v108, v109
	global_store_dwordx4 v[114:115], v[98:101], off
	v_cvt_f32_i32_e32 v16, v16
	v_cvt_f32_i32_e32 v11, v11
	v_rcp_f32_e32 v100, v214
	v_add_u32_e32 v99, 32, v149
	v_mul_f32_e32 v98, v137, v151
	v_pk_mul_f32 v[86:87], v[98:99], v[86:87] op_sel_hi:[0,1]
	v_rcp_f32_e32 v101, v215
	v_pk_mul_f32 v[216:217], v[96:97], s[100:101] op_sel_hi:[1,0]
	v_exp_f32_e32 v216, v216
	v_exp_f32_e32 v217, v217
	v_pk_mul_f32 v[88:89], v[98:99], v[88:89] op_sel_hi:[0,1]
	v_pk_mul_f32 v[94:95], v[94:95], v[100:101]
	v_pk_mul_f32 v[82:83], v[98:99], v[82:83] op_sel_hi:[0,1]
	v_pk_add_f32 v[216:217], v[216:217], 1.0 op_sel_hi:[1,0]
	v_rcp_f32_e32 v102, v216
	v_pk_mul_f32 v[86:87], v[86:87], v[94:95]
	v_pk_mul_f32 v[84:85], v[98:99], v[84:85] op_sel_hi:[0,1]
	v_mad_i64_i32 v[98:99], s[24:25], v99, s52, v[130:131]
	v_rcp_f32_e32 v103, v217
	v_pk_mul_f32 v[218:219], v[90:91], s[100:101] op_sel_hi:[1,0]
	v_exp_f32_e32 v218, v218
	v_exp_f32_e32 v219, v219
	v_cvt_f32_i32_e32 v10, v10
	v_pk_mul_f32 v[96:97], v[96:97], v[102:103]
	v_cvt_f32_i32_e32 v13, v13
	v_pk_add_f32 v[218:219], v[218:219], 1.0 op_sel_hi:[1,0]
	v_rcp_f32_e32 v94, v218
	v_pk_mul_f32 v[88:89], v[88:89], v[96:97]
	v_cvt_f32_i32_e32 v12, v12
	v_cvt_f32_i32_e32 v21, v21
	v_rcp_f32_e32 v95, v219
	v_pk_mul_f32 v[220:221], v[92:93], s[100:101] op_sel_hi:[1,0]
	v_exp_f32_e32 v220, v220
	v_exp_f32_e32 v221, v221
	v_cvt_f32_i32_e32 v20, v20
	v_pk_mul_f32 v[90:91], v[90:91], v[94:95]
	v_cvt_f32_i32_e32 v19, v19
	v_pk_add_f32 v[220:221], v[220:221], 1.0 op_sel_hi:[1,0]
	v_rcp_f32_e32 v96, v220
	v_cvt_f32_i32_e32 v18, v18
	v_cvt_f32_i32_e32 v7, v7
	v_cvt_f32_i32_e32 v6, v6
	v_rcp_f32_e32 v97, v221
	v_mul_f32_e32 v0, v138, v150
	v_pk_mul_f32 v[78:79], v[0:1], v[78:79] op_sel_hi:[0,1]
	v_pk_mul_f32 v[80:81], v[0:1], v[80:81] op_sel_hi:[0,1]
	v_pk_mul_f32 v[76:77], v[0:1], v[76:77] op_sel_hi:[0,1]
	v_pk_mul_f32 v[74:75], v[0:1], v[74:75] op_sel_hi:[0,1]
	v_pk_mul_f32 v[222:223], v[78:79], s[100:101] op_sel_hi:[1,0]
	v_exp_f32_e32 v222, v222
	v_exp_f32_e32 v223, v223
	v_pk_mul_f32 v[92:93], v[92:93], v[96:97]
	v_cvt_f32_i32_e32 v9, v9
	v_pk_mul_f32 v[92:93], v[84:85], v[92:93]
	v_pk_mul_f32 v[84:85], v[82:83], v[90:91]
	v_cvt_pk_bf16_f32 v82, v86, v87
	v_cvt_pk_bf16_f32 v83, v88, v89
	v_pk_add_f32 v[222:223], v[222:223], 1.0 op_sel_hi:[1,0]
	v_cvt_pk_bf16_f32 v84, v84, v85
	v_cvt_pk_bf16_f32 v85, v92, v93
	global_store_dwordx4 v[98:99], v[82:85], off
	v_cvt_f32_i32_e32 v8, v8
	v_cvt_f32_i32_e32 v5, v5
	v_rcp_f32_e32 v84, v222
	v_add_u32_e32 v83, 48, v149
	v_mul_f32_e32 v82, v138, v151
	v_pk_mul_f32 v[70:71], v[82:83], v[70:71] op_sel_hi:[0,1]
	v_rcp_f32_e32 v85, v223
	v_pk_mul_f32 v[224:225], v[80:81], s[100:101] op_sel_hi:[1,0]
	v_exp_f32_e32 v224, v224
	v_exp_f32_e32 v225, v225
	v_pk_mul_f32 v[72:73], v[82:83], v[72:73] op_sel_hi:[0,1]
	v_pk_mul_f32 v[78:79], v[78:79], v[84:85]
	v_pk_mul_f32 v[66:67], v[82:83], v[66:67] op_sel_hi:[0,1]
	v_pk_add_f32 v[224:225], v[224:225], 1.0 op_sel_hi:[1,0]
	v_rcp_f32_e32 v86, v224
	v_pk_mul_f32 v[70:71], v[70:71], v[78:79]
	v_pk_mul_f32 v[68:69], v[82:83], v[68:69] op_sel_hi:[0,1]
	v_mad_i64_i32 v[82:83], s[24:25], v83, s52, v[130:131]
	v_rcp_f32_e32 v87, v225
	v_pk_mul_f32 v[226:227], v[74:75], s[100:101] op_sel_hi:[1,0]
	v_exp_f32_e32 v226, v226
	v_exp_f32_e32 v227, v227
	v_cvt_f32_i32_e32 v4, v4
	v_pk_mul_f32 v[80:81], v[80:81], v[86:87]
	v_cvt_f32_i32_e32 v3, v3
	v_pk_add_f32 v[226:227], v[226:227], 1.0 op_sel_hi:[1,0]
	v_rcp_f32_e32 v78, v226
	v_pk_mul_f32 v[72:73], v[72:73], v[80:81]
	v_cvt_f32_i32_e32 v2, v2
	s_andn2_b64 vcc, exec, s[22:23]
	v_rcp_f32_e32 v79, v227
	v_pk_mul_f32 v[228:229], v[76:77], s[100:101] op_sel_hi:[1,0]
	v_exp_f32_e32 v228, v228
	v_exp_f32_e32 v229, v229
	v_pk_mul_f32 v[74:75], v[74:75], v[78:79]
	v_pk_add_f32 v[228:229], v[228:229], 1.0 op_sel_hi:[1,0]
	v_rcp_f32_e32 v80, v228
	s_nop 0
	v_rcp_f32_e32 v81, v229
	v_mul_f32_e32 v0, v139, v150
	v_pk_mul_f32 v[62:63], v[0:1], v[62:63] op_sel_hi:[0,1]
	v_pk_mul_f32 v[64:65], v[0:1], v[64:65] op_sel_hi:[0,1]
	v_pk_mul_f32 v[60:61], v[0:1], v[60:61] op_sel_hi:[0,1]
	v_pk_mul_f32 v[58:59], v[0:1], v[58:59] op_sel_hi:[0,1]
	v_pk_mul_f32 v[214:215], v[62:63], s[100:101] op_sel_hi:[1,0]
	v_exp_f32_e32 v214, v214
	v_exp_f32_e32 v215, v215
	v_pk_mul_f32 v[76:77], v[76:77], v[80:81]
	v_pk_add_f32 v[214:215], v[214:215], 1.0 op_sel_hi:[1,0]
	v_pk_mul_f32 v[76:77], v[68:69], v[76:77]
	v_pk_mul_f32 v[68:69], v[66:67], v[74:75]
	v_cvt_pk_bf16_f32 v66, v70, v71
	v_cvt_pk_bf16_f32 v67, v72, v73
	s_nop 0
	v_cvt_pk_bf16_f32 v68, v68, v69
	v_cvt_pk_bf16_f32 v69, v76, v77
	global_store_dwordx4 v[82:83], v[66:69], off
	s_nop 1
	v_rcp_f32_e32 v68, v214
	v_add_u32_e32 v67, 0x80, v149
	v_mul_f32_e32 v66, v139, v151
	v_pk_mul_f32 v[54:55], v[66:67], v[54:55] op_sel_hi:[0,1]
	v_rcp_f32_e32 v69, v215
	v_pk_mul_f32 v[216:217], v[64:65], s[100:101] op_sel_hi:[1,0]
	v_exp_f32_e32 v216, v216
	v_exp_f32_e32 v217, v217
	v_pk_mul_f32 v[56:57], v[66:67], v[56:57] op_sel_hi:[0,1]
	v_pk_mul_f32 v[62:63], v[62:63], v[68:69]
	v_pk_mul_f32 v[50:51], v[66:67], v[50:51] op_sel_hi:[0,1]
	v_pk_add_f32 v[216:217], v[216:217], 1.0 op_sel_hi:[1,0]
	v_rcp_f32_e32 v70, v216
	v_pk_mul_f32 v[54:55], v[54:55], v[62:63]
	v_pk_mul_f32 v[52:53], v[66:67], v[52:53] op_sel_hi:[0,1]
	v_mad_i64_i32 v[66:67], s[24:25], v67, s52, v[130:131]
	v_rcp_f32_e32 v71, v217
	v_pk_mul_f32 v[218:219], v[58:59], s[100:101] op_sel_hi:[1,0]
	v_exp_f32_e32 v218, v218
	v_exp_f32_e32 v219, v219
	v_pk_mul_f32 v[64:65], v[64:65], v[70:71]
	s_nop 0
	v_pk_mul_f32 v[56:57], v[56:57], v[64:65]
	v_pk_add_f32 v[218:219], v[218:219], 1.0 op_sel_hi:[1,0]
	v_rcp_f32_e32 v62, v218
	s_nop 0
	v_rcp_f32_e32 v63, v219
	v_pk_mul_f32 v[220:221], v[60:61], s[100:101] op_sel_hi:[1,0]
	v_exp_f32_e32 v220, v220
	v_exp_f32_e32 v221, v221
	v_pk_mul_f32 v[58:59], v[58:59], v[62:63]
	v_pk_add_f32 v[220:221], v[220:221], 1.0 op_sel_hi:[1,0]
	v_rcp_f32_e32 v64, v220
	s_nop 0
	v_rcp_f32_e32 v65, v221
	v_mul_f32_e32 v0, v140, v150
	v_pk_mul_f32 v[46:47], v[0:1], v[46:47] op_sel_hi:[0,1]
	v_pk_mul_f32 v[48:49], v[0:1], v[48:49] op_sel_hi:[0,1]
	v_pk_mul_f32 v[44:45], v[0:1], v[44:45] op_sel_hi:[0,1]
	v_pk_mul_f32 v[42:43], v[0:1], v[42:43] op_sel_hi:[0,1]
	v_pk_mul_f32 v[222:223], v[46:47], s[100:101] op_sel_hi:[1,0]
	v_exp_f32_e32 v222, v222
	v_exp_f32_e32 v223, v223
	v_pk_mul_f32 v[60:61], v[60:61], v[64:65]
	v_pk_add_f32 v[222:223], v[222:223], 1.0 op_sel_hi:[1,0]
	v_pk_mul_f32 v[60:61], v[52:53], v[60:61]
	v_pk_mul_f32 v[52:53], v[50:51], v[58:59]
	v_cvt_pk_bf16_f32 v50, v54, v55
	v_cvt_pk_bf16_f32 v51, v56, v57
	s_nop 0
	v_cvt_pk_bf16_f32 v52, v52, v53
	v_cvt_pk_bf16_f32 v53, v60, v61
	global_store_dwordx4 v[66:67], v[50:53], off
	s_nop 1
	v_rcp_f32_e32 v52, v222
	v_add_u32_e32 v51, 0x90, v149
	v_mul_f32_e32 v50, v140, v151
	v_pk_mul_f32 v[38:39], v[50:51], v[38:39] op_sel_hi:[0,1]
	v_rcp_f32_e32 v53, v223
	v_pk_mul_f32 v[224:225], v[48:49], s[100:101] op_sel_hi:[1,0]
	v_exp_f32_e32 v224, v224
	v_exp_f32_e32 v225, v225
	v_pk_mul_f32 v[40:41], v[50:51], v[40:41] op_sel_hi:[0,1]
	v_pk_mul_f32 v[46:47], v[46:47], v[52:53]
	v_pk_mul_f32 v[34:35], v[50:51], v[34:35] op_sel_hi:[0,1]
	v_pk_add_f32 v[224:225], v[224:225], 1.0 op_sel_hi:[1,0]
	v_rcp_f32_e32 v54, v224
	v_pk_mul_f32 v[38:39], v[38:39], v[46:47]
	v_pk_mul_f32 v[36:37], v[50:51], v[36:37] op_sel_hi:[0,1]
	v_mad_i64_i32 v[50:51], s[24:25], v51, s52, v[130:131]
	v_rcp_f32_e32 v55, v225
	v_pk_mul_f32 v[226:227], v[42:43], s[100:101] op_sel_hi:[1,0]
	v_exp_f32_e32 v226, v226
	v_exp_f32_e32 v227, v227
	v_pk_mul_f32 v[48:49], v[48:49], v[54:55]
	s_nop 0
	v_pk_mul_f32 v[40:41], v[40:41], v[48:49]
	v_pk_add_f32 v[226:227], v[226:227], 1.0 op_sel_hi:[1,0]
	v_rcp_f32_e32 v46, v226
	s_nop 0
	v_rcp_f32_e32 v47, v227
	v_pk_mul_f32 v[228:229], v[44:45], s[100:101] op_sel_hi:[1,0]
	v_exp_f32_e32 v228, v228
	v_exp_f32_e32 v229, v229
	v_pk_mul_f32 v[42:43], v[42:43], v[46:47]
	v_pk_add_f32 v[228:229], v[228:229], 1.0 op_sel_hi:[1,0]
	v_rcp_f32_e32 v48, v228
	s_nop 0
	v_rcp_f32_e32 v49, v229
	v_mul_f32_e32 v0, v141, v150
	v_pk_mul_f32 v[30:31], v[0:1], v[30:31] op_sel_hi:[0,1]
	v_pk_mul_f32 v[32:33], v[0:1], v[32:33] op_sel_hi:[0,1]
	v_pk_mul_f32 v[28:29], v[0:1], v[28:29] op_sel_hi:[0,1]
	v_pk_mul_f32 v[26:27], v[0:1], v[26:27] op_sel_hi:[0,1]
	v_pk_mul_f32 v[214:215], v[30:31], s[100:101] op_sel_hi:[1,0]
	v_exp_f32_e32 v214, v214
	v_exp_f32_e32 v215, v215
	v_pk_mul_f32 v[44:45], v[44:45], v[48:49]
	v_pk_add_f32 v[214:215], v[214:215], 1.0 op_sel_hi:[1,0]
	v_pk_mul_f32 v[44:45], v[36:37], v[44:45]
	v_pk_mul_f32 v[36:37], v[34:35], v[42:43]
	v_cvt_pk_bf16_f32 v34, v38, v39
	v_cvt_pk_bf16_f32 v35, v40, v41
	s_nop 0
	v_cvt_pk_bf16_f32 v36, v36, v37
	v_cvt_pk_bf16_f32 v37, v44, v45
	global_store_dwordx4 v[50:51], v[34:37], off
	s_nop 1
	v_rcp_f32_e32 v36, v214
	v_add_u32_e32 v35, 0xa0, v149
	v_mul_f32_e32 v34, v141, v151
	v_pk_mul_f32 v[22:23], v[34:35], v[22:23] op_sel_hi:[0,1]
	v_rcp_f32_e32 v37, v215
	v_pk_mul_f32 v[216:217], v[32:33], s[100:101] op_sel_hi:[1,0]
	v_exp_f32_e32 v216, v216
	v_exp_f32_e32 v217, v217
	v_pk_mul_f32 v[24:25], v[34:35], v[24:25] op_sel_hi:[0,1]
	v_pk_mul_f32 v[30:31], v[30:31], v[36:37]
	v_pk_mul_f32 v[18:19], v[34:35], v[18:19] op_sel_hi:[0,1]
	v_pk_add_f32 v[216:217], v[216:217], 1.0 op_sel_hi:[1,0]
	v_rcp_f32_e32 v38, v216
	v_pk_mul_f32 v[22:23], v[22:23], v[30:31]
	v_pk_mul_f32 v[20:21], v[34:35], v[20:21] op_sel_hi:[0,1]
	v_mad_i64_i32 v[34:35], s[24:25], v35, s52, v[130:131]
	v_rcp_f32_e32 v39, v217
	v_pk_mul_f32 v[218:219], v[26:27], s[100:101] op_sel_hi:[1,0]
	v_exp_f32_e32 v218, v218
	v_exp_f32_e32 v219, v219
	v_pk_mul_f32 v[32:33], v[32:33], v[38:39]
	s_nop 0
	v_pk_mul_f32 v[24:25], v[24:25], v[32:33]
	v_pk_add_f32 v[218:219], v[218:219], 1.0 op_sel_hi:[1,0]
	v_rcp_f32_e32 v30, v218
	s_nop 0
	v_rcp_f32_e32 v31, v219
	v_pk_mul_f32 v[220:221], v[28:29], s[100:101] op_sel_hi:[1,0]
	v_exp_f32_e32 v220, v220
	v_exp_f32_e32 v221, v221
	v_pk_mul_f32 v[26:27], v[26:27], v[30:31]
	v_pk_add_f32 v[220:221], v[220:221], 1.0 op_sel_hi:[1,0]
	v_rcp_f32_e32 v32, v220
	s_nop 0
	v_rcp_f32_e32 v33, v221
	v_mul_f32_e32 v0, v142, v150
	v_pk_mul_f32 v[14:15], v[0:1], v[14:15] op_sel_hi:[0,1]
	v_pk_mul_f32 v[16:17], v[0:1], v[16:17] op_sel_hi:[0,1]
	v_pk_mul_f32 v[12:13], v[0:1], v[12:13] op_sel_hi:[0,1]
	v_pk_mul_f32 v[10:11], v[0:1], v[10:11] op_sel_hi:[0,1]
	v_pk_mul_f32 v[222:223], v[14:15], s[100:101] op_sel_hi:[1,0]
	v_exp_f32_e32 v222, v222
	v_exp_f32_e32 v223, v223
	v_pk_mul_f32 v[28:29], v[28:29], v[32:33]
	v_pk_add_f32 v[222:223], v[222:223], 1.0 op_sel_hi:[1,0]
	v_pk_mul_f32 v[28:29], v[20:21], v[28:29]
	v_pk_mul_f32 v[20:21], v[18:19], v[26:27]
	v_cvt_pk_bf16_f32 v18, v22, v23
	v_cvt_pk_bf16_f32 v19, v24, v25
	s_nop 0
	v_cvt_pk_bf16_f32 v20, v20, v21
	v_cvt_pk_bf16_f32 v21, v28, v29
	global_store_dwordx4 v[34:35], v[18:21], off
	s_nop 1
	v_rcp_f32_e32 v20, v222
	v_add_u32_e32 v19, 0xb0, v149
	v_mul_f32_e32 v18, v142, v151
	v_pk_mul_f32 v[6:7], v[18:19], v[6:7] op_sel_hi:[0,1]
	v_rcp_f32_e32 v21, v223
	v_pk_mul_f32 v[224:225], v[16:17], s[100:101] op_sel_hi:[1,0]
	v_exp_f32_e32 v224, v224
	v_exp_f32_e32 v225, v225
	v_pk_mul_f32 v[8:9], v[18:19], v[8:9] op_sel_hi:[0,1]
	v_pk_mul_f32 v[14:15], v[14:15], v[20:21]
	v_pk_mul_f32 v[2:3], v[18:19], v[2:3] op_sel_hi:[0,1]
	v_pk_add_f32 v[224:225], v[224:225], 1.0 op_sel_hi:[1,0]
	v_rcp_f32_e32 v22, v224
	v_pk_mul_f32 v[6:7], v[6:7], v[14:15]
	v_pk_mul_f32 v[4:5], v[18:19], v[4:5] op_sel_hi:[0,1]
	v_mad_i64_i32 v[18:19], s[24:25], v19, s52, v[130:131]
	v_rcp_f32_e32 v23, v225
	v_pk_mul_f32 v[226:227], v[10:11], s[100:101] op_sel_hi:[1,0]
	v_exp_f32_e32 v226, v226
	v_exp_f32_e32 v227, v227
	s_mov_b64 s[24:25], -1
	v_pk_mul_f32 v[16:17], v[16:17], v[22:23]
	v_pk_add_f32 v[226:227], v[226:227], 1.0 op_sel_hi:[1,0]
	v_rcp_f32_e32 v14, v226
	v_pk_mul_f32 v[8:9], v[8:9], v[16:17]
	v_rcp_f32_e32 v15, v227
	v_pk_mul_f32 v[228:229], v[12:13], s[100:101] op_sel_hi:[1,0]
	v_exp_f32_e32 v228, v228
	v_exp_f32_e32 v229, v229
	v_pk_mul_f32 v[10:11], v[10:11], v[14:15]
	v_pk_add_f32 v[228:229], v[228:229], 1.0 op_sel_hi:[1,0]
	v_rcp_f32_e32 v16, v228
	s_nop 0
	v_rcp_f32_e32 v17, v229
	s_nop 0
	v_pk_mul_f32 v[12:13], v[12:13], v[16:17]
	s_nop 0
	v_pk_mul_f32 v[12:13], v[4:5], v[12:13]
	v_pk_mul_f32 v[4:5], v[2:3], v[10:11]
	v_cvt_pk_bf16_f32 v2, v6, v7
	v_cvt_pk_bf16_f32 v3, v8, v9
	s_nop 0
	v_cvt_pk_bf16_f32 v4, v4, v5
	v_cvt_pk_bf16_f32 v5, v12, v13
	global_store_dwordx4 v[18:19], v[2:5], off
	s_cbranch_vccnz .LBB0_441
	s_cmp_eq_u32 s83, s71
	s_cbranch_scc1 .LBB0_451
	v_lshl_add_u32 v2, s83, 8, v146
	v_ashrrev_i32_e32 v3, 31, v2
	v_lshl_add_u64 v[2:3], v[2:3], 2, s[4:5]
	global_load_dword v135, v[2:3], off sc1
	global_load_dword v136, v[2:3], off offset:64 sc1
	global_load_dword v137, v[2:3], off offset:128 sc1
	global_load_dword v138, v[2:3], off offset:192 sc1
	global_load_dword v139, v[2:3], off offset:512 sc1
	global_load_dword v140, v[2:3], off offset:576 sc1
	global_load_dword v141, v[2:3], off offset:640 sc1
	global_load_dword v142, v[2:3], off offset:704 sc1

	.amdhsa_kernel _Z8mega_fwd4Args
		.amdhsa_group_segment_fixed_size 0
		.amdhsa_private_segment_fixed_size 0
		.amdhsa_kernarg_size 480
		.amdhsa_user_sgpr_count 2
		.amdhsa_user_sgpr_dispatch_ptr 0
		.amdhsa_user_sgpr_queue_ptr 0
		.amdhsa_user_sgpr_kernarg_segment_ptr 1
		.amdhsa_user_sgpr_dispatch_id 0
		.amdhsa_user_sgpr_kernarg_preload_length 0
		.amdhsa_user_sgpr_kernarg_preload_offset 0
		.amdhsa_user_sgpr_private_segment_size 0
		.amdhsa_uses_dynamic_stack 0
		.amdhsa_enable_private_segment 0
		.amdhsa_system_sgpr_workgroup_id_x 1
		.amdhsa_system_sgpr_workgroup_id_y 0
		.amdhsa_system_sgpr_workgroup_id_z 0
		.amdhsa_system_sgpr_workgroup_info 0
		.amdhsa_system_vgpr_workitem_id 0
		.amdhsa_next_free_vgpr 256
		.amdhsa_next_free_sgpr 102
		.amdhsa_accum_offset 256
		.amdhsa_reserve_vcc 1
		.amdhsa_float_round_mode_32 0
		.amdhsa_float_round_mode_16_64 0
		.amdhsa_float_denorm_mode_32 3
		.amdhsa_float_denorm_mode_16_64 3
		.amdhsa_dx10_clamp 1
		.amdhsa_ieee_mode 1
		.amdhsa_fp16_overflow 0
		.amdhsa_tg_split 0
		.amdhsa_exception_fp_ieee_invalid_op 0
		.amdhsa_exception_fp_denorm_src 0
		.amdhsa_exception_fp_ieee_div_zero 0
		.amdhsa_exception_fp_ieee_overflow 0
		.amdhsa_exception_fp_ieee_underflow 0
		.amdhsa_exception_fp_ieee_inexact 0
		.amdhsa_exception_int_div_zero 0
	.end_amdhsa_kernel

amdhsa.kernels:
  - .agpr_count:     0
    .args:
      - .offset:         0
        .size:           224
        .value_kind:     by_value
      - .offset:         224
        .size:           4
        .value_kind:     hidden_block_count_x
      - .offset:         228
        .size:           4
        .value_kind:     hidden_block_count_y
      - .offset:         232
        .size:           4
        .value_kind:     hidden_block_count_z
      - .offset:         236
        .size:           2
        .value_kind:     hidden_group_size_x
      - .offset:         238
        .size:           2
        .value_kind:     hidden_group_size_y
      - .offset:         240
        .size:           2
        .value_kind:     hidden_group_size_z
      - .offset:         242
        .size:           2
        .value_kind:     hidden_remainder_x
      - .offset:         244
        .size:           2
        .value_kind:     hidden_remainder_y
      - .offset:         246
        .size:           2
        .value_kind:     hidden_remainder_z
      - .offset:         264
        .size:           8
        .value_kind:     hidden_global_offset_x
      - .offset:         272
        .size:           8
        .value_kind:     hidden_global_offset_y
      - .offset:         280
        .size:           8
        .value_kind:     hidden_global_offset_z
      - .offset:         288
        .size:           2
        .value_kind:     hidden_grid_dims
      - .offset:         344
        .size:           4
        .value_kind:     hidden_dynamic_lds_size
    .group_segment_fixed_size: 0
    .kernarg_segment_align: 8
    .kernarg_segment_size: 480
    .language:       OpenCL C
    .language_version:
      - 2
      - 0
    .max_flat_workgroup_size: 512
    .name:           _Z8mega_fwd4Args
    .private_segment_fixed_size: 0
    .sgpr_count:     108
    .sgpr_spill_count: 44
    .symbol:         _Z8mega_fwd4Args.kd
    .uniform_work_group_size: 1
    .uses_dynamic_stack: false
    .vgpr_count:     256
    .vgpr_spill_count: 0
    .wavefront_size: 64
